# LN1 layer-1 path: issue the XB lo/hi and MIX row loads together, counted waits, instead of three sequential round trips
# baseline (speedup 1.0000x reference)
; DEV float lo_f(unsigned w) { return __uint_as_float(w << 16); }
; DEV float hi_f(unsigned w) { return __uint_as_float(w & 0xFFFF0000u); }
; __device__ void ln1_phase(const Params& P, int l) {
;     ...
;       if (l == 0) {
;         const float* xr = P.x + (size_t)t * 1024 + hsel * 512 + lane * 8;
;         const float4 a = *(const float4*)xr, b = *(const float4*)(xr + 4);
;         r[0] = a.x; r[1] = a.y; r[2] = a.z; r[3] = a.w; r[4] = b.x; r[5] = b.y; r[6] = b.z; r[7] = b.w;
;       } else {
;         const uint4 xx = *(const uint4*)(xb + hsel * 512 + lane * 8);
;         r[0] = lo_f(xx.x); r[1] = hi_f(xx.x); r[2] = lo_f(xx.y); r[3] = hi_f(xx.y); r[4] = lo_f(xx.z); r[5] = hi_f(xx.z); r[6] = lo_f(xx.w); r[7] = hi_f(xx.w);
;       }
;       const uint4 mm = *(const uint4*)(mx + hsel * 512 + lane * 8);
.LBB0_56:
	v_ashrrev_i32_e32 v31, 31, v30
	v_lshlrev_b64 v[0:1], 11, v[30:31]
	v_lshl_add_u64 v[32:33], v[28:29], 0, v[0:1]
	s_and_b64 vcc, exec, s[6:7]
	s_cbranch_vccz .Lln1_l0
	v_lshlrev_b64 v[8:9], 10, v[30:31]
	v_lshl_add_u64 v[34:35], v[8:9], 1, v[20:21]
	global_load_dwordx4 v[4:7], v[32:33], off
	global_load_dwordx4 v[12:15], v[32:33], off offset:1024
	global_load_dwordx4 v[16:19], v[34:35], off
	s_waitcnt vmcnt(2)
	v_lshlrev_b32_e32 v0, 16, v4
	v_and_b32_e32 v1, 0xffff0000, v4
	v_lshlrev_b32_e32 v2, 16, v5
	v_and_b32_e32 v3, 0xffff0000, v5
	v_lshlrev_b32_e32 v4, 16, v6
	v_and_b32_e32 v5, 0xffff0000, v6
	v_lshlrev_b32_e32 v6, 16, v7
	v_and_b32_e32 v7, 0xffff0000, v7
	s_waitcnt vmcnt(1)
	v_lshlrev_b32_e32 v8, 16, v12
	v_and_b32_e32 v9, 0xffff0000, v12
	v_lshlrev_b32_e32 v10, 16, v13
	v_and_b32_e32 v11, 0xffff0000, v13
	v_lshlrev_b32_e32 v12, 16, v14
	v_and_b32_e32 v13, 0xffff0000, v14
	v_lshlrev_b32_e32 v14, 16, v15
	v_and_b32_e32 v15, 0xffff0000, v15
	s_branch .LBB0_55
.Lln1_l0:
	s_mov_b64 s[0:1], -1
